# LRU gates: 2x folded into c8 (exact), i-gate fma/+1 packed; on top of fixup unroll
# baseline (speedup 1.0000x reference)
; __device__ __forceinline__ void mix_phase(LAS unsigned char* lds, const Params& p, const int layer) {
;     ...
;                     const float rg = mix_sigmoid(accr[m][j] + bav), ig = mix_sigmoid(acci[m][j] + bxv), la = -rg * c8v, x2 = 2.0f * la;
;                     const float Pj = __expf(la);
;                     const float q_ = 1.f + x2 * (0.5f + x2 * (1.f / 6 + x2 * (1.f / 24 + x2 * (1.f / 120 + x2 * (1.f / 720 + x2 * (1.f / 5040))))));
;                     const float om = (x2 > -0.3f) ? -x2 * q_ : 1.0f - Pj * Pj;
;                     P_[j] = Pj; h_[j] = __builtin_amdgcn_sqrtf(om) * (ig * xa); }
; #pragma unroll
;                 for (int j = 1; j < 4; ++j) { h_[j] = P_[j] * h_[j - 1] + h_[j]; P_[j] = P_[j] * P_[j - 1]; }
;                 float Pg = P_[3], Hg = h_[3];
;                 { const float Pu = __shfl_up(Pg, 16), Hu = __shfl_up(Hg, 16); if (gq >= 1) { Hg = Pg * Hu + Hg; Pg = Pg * Pu; } }
;                 { const float Pu = __shfl_up(Pg, 32), Hu = __shfl_up(Hg, 32); if (gq >= 2) { Hg = Pg * Hu + Hg; Pg = Pg * Pu; } }
;                 float Pe = __shfl_up(Pg, 16), He = __shfl_up(Hg, 16); if (gq == 0) { Pe = 1.f; He = 0.f; }
;                 const float Hcm = prt ? Hc : h0s[m];
;                 const float Hin = Pe * Hcm + He, Pin = Pe * Pc;
; #pragma unroll
;                 for (int j = 0; j < 4; ++j) { hl[m][j] = h_[j] + P_[j] * Hin; pl[m][j] = P_[j] * Pin; }
;                 const float hb = __shfl(hl[m][3], 48 + fr), pb_ = __shfl(pl[m][3], 48 + fr);
;                 Hc = prt ? hb : 0.f; Pc = prt ? pb_ : 1.f;
;             }
;             if (!prt && (fq & 1)) {
; #pragma unroll
;                 for (int m = 0; m < 4; ++m) out[O_HS + (size_t)(layer * 128 + ((r0 - NP) >> 3) + 2 * m + (fq >> 1)) * LW + ch] = hl[m][3];
;             }
;                 if (prt) {
;                 const int b_ = r0 >> 11, c_ = (r0 & 2047) >> 6;
;                 const unsigned tag = (unsigned)layer + 1u;
;                 unsigned long long* T1 = (unsigned long long*)(ws + WS_TOT2) + (size_t)(b_ * 32) * LW + ch;
;                 unsigned* PF = (unsigned*)(ws + WS_PREF2) + (size_t)(b_ * 32) * LW + ch;
;                 if (fq == 0) __hip_atomic_store(T1 + (size_t)c_ * LW, ((unsigned long long)__float_as_uint(Hc) << 32) | (unsigned long long)((__float_as_uint(Pc) & ~3u) | tag), RLX_AGENT);
.LBB0_406:
	v_lshlrev_b32_e32 v0, 3, v137
	v_lshlrev_b32_e32 v66, 4, v130
	v_lshlrev_b32_e32 v70, 1, v0
	v_lshrrev_b32_e32 v0, 1, v137
	v_readlane_b32 s3, v248, 33
	v_and_b32_e32 v140, 0x70, v66
	v_and_b32_e32 v66, 64, v223
	v_or_b32_e32 v228, s3, v0
	v_add_u32_e32 v0, -16, v223
	v_cmp_lt_i32_e32 vcc, v0, v66
	v_ashrrev_i32_e32 v133, 31, v132
	s_mov_b64 s[6:7], 0x26308000
	v_cndmask_b32_e32 v0, v0, v223, vcc
	v_lshlrev_b32_e32 v229, 2, v0
	v_subrev_u32_e32 v0, 32, v223
	v_cmp_lt_i32_e32 vcc, v0, v66
	s_add_i32 s2, s56, 1
	v_readlane_b32 s5, v248, 3
	v_cndmask_b32_e32 v0, v0, v223, vcc
	v_lshlrev_b32_e32 v230, 2, v0
	v_or_b32_e32 v0, v66, v135
	v_lshl_add_u64 v[66:67], v[132:133], 3, s[14:15]
	v_lshl_add_u64 v[142:143], v[66:67], 0, s[6:7]
	v_lshlrev_b64 v[66:67], 2, v[132:133]
	v_lshlrev_b32_e32 v231, 2, v0
	v_lshl_add_u64 v[68:69], s[14:15], 0, v[66:67]
	s_mov_b64 s[6:7], 0x26508000
	v_readlane_b32 s56, v251, 21
	v_lshlrev_b32_e32 v0, 2, v136
	v_ashrrev_i32_e32 v139, 3, v130
	v_bfe_u32 v227, v130, 4, 1
	v_lshl_add_u32 v233, v134, 2, s5
	v_lshl_add_u64 v[144:145], v[68:69], 0, s[6:7]
	s_movk_i32 s5, 0x210
	v_mul_u32_u24_e32 v68, 0x110, v135
	v_readlane_b32 s57, v251, 22
	v_readlane_b32 s64, v251, 29
	v_readlane_b32 s65, v251, 30
	v_readlane_b32 s36, v248, 35
	v_lshl_add_u64 v[148:149], s[0:1], 0, v[0:1]
	v_readlane_b32 s0, v248, 5
	s_mov_b32 s3, 0
	v_or_b32_e32 v232, 0xc0, v231
	v_cmp_eq_u32_e64 s[38:39], 0, v227
	v_cmp_eq_u32_e64 s[40:41], 0, v137
	v_mul_lo_u32 v234, v139, s5
	v_mul_u32_u24_e32 v235, 0x840, v137
	v_mul_lo_u32 v236, v226, s5
	v_or_b32_e32 v237, 64, v231
	v_or_b32_e32 v238, 0x80, v231
	v_readlane_b32 s37, v248, 36
	v_readlane_b32 s56, v248, 31
	v_lshl_add_u64 v[146:147], s[64:65], 0, v[66:67]
	v_add3_u32 v239, s0, v70, v68
	v_lshlrev_b32_e32 v150, 1, v140
	v_lshlrev_b32_e32 v152, 1, v134
	s_mov_b32 s5, 0
	v_readlane_b32 s12, v251, 0
	s_waitcnt lgkmcnt(0)
	s_barrier
	v_readlane_b32 s58, v251, 23
	v_readlane_b32 s59, v251, 24
	v_readlane_b32 s60, v251, 25
	v_readlane_b32 s61, v251, 26
	v_readlane_b32 s62, v251, 27
	v_readlane_b32 s63, v251, 28
	v_readlane_b32 s66, v251, 31
	v_readlane_b32 s67, v251, 32
	v_readlane_b32 s68, v251, 33
	v_readlane_b32 s69, v251, 34
	v_readlane_b32 s70, v251, 35
	v_readlane_b32 s71, v251, 36
	v_readlane_b32 s57, v248, 32
	s_waitcnt vmcnt(0)
	v_mul_f32_e32 v242, 0xbfb8aa3b, v179
	v_mul_f32_e32 v243, 0xbfb8aa3b, v224
	v_add_f32_e32 v225, v225, v225
	v_mov_b32_e32 v244, 1.0
	s_branch .LBB0_409

; __device__ __forceinline__ void mix_phase(LAS unsigned char* lds, const Params& p, const int layer) {
;     ...
;             for (int u = u0; u < NUB; u += G) {
;                 const int s_ = u >> 4, r0 = mix_tile_row0(s_);
;                 const bool prt = s_ < 128;
.LBB0_409:
	s_mov_b32 s100, 0
	s_mov_b32 s98, 0xbfb8aa3b
	s_mov_b32 s99, 0xbfb8aa3b
	s_ashr_i32 s6, s12, 4
	s_cmpk_lt_i32 s6, 0x80
	s_cselect_b64 s[42:43], -1, 0
	s_cmpk_gt_i32 s6, 0x7f
	s_cselect_b64 s[0:1], -1, 0
	s_mov_b64 s[20:21], -1
	s_and_b64 vcc, exec, s[0:1]
	s_cbranch_vccz .LBB0_411
	s_lshl_b32 s7, s6, 6
	s_mov_b64 s[20:21], 0

; __device__ __forceinline__ float mix_sigmoid(float v) { return __builtin_amdgcn_rcpf(1.0f + __expf(-v)); }
; __device__ __forceinline__ void mix_phase(LAS unsigned char* lds, const Params& p, const int layer) {
;     ...
;             for (int m = 0; m < 4; ++m) {
;                 float h_[4], P_[4];
; #pragma unroll
;                 for (int j = 0; j < 4; ++j) { const float xa = XC[(m * 16 + fq * 4 + j) * 132 + cw + fr];
;                     const float rg = mix_sigmoid(accr[m][j] + bav), ig = mix_sigmoid(acci[m][j] + bxv), la = -rg * c8v, x2 = 2.0f * la;
;                     const float Pj = __expf(la);
;                     const float q_ = 1.f + x2 * (0.5f + x2 * (1.f / 6 + x2 * (1.f / 24 + x2 * (1.f / 120 + x2 * (1.f / 720 + x2 * (1.f / 5040))))));
;                     const float om = (x2 > -0.3f) ? -x2 * q_ : 1.0f - Pj * Pj;
;                     P_[j] = Pj; h_[j] = __builtin_amdgcn_sqrtf(om) * (ig * xa); }
; #pragma unroll
;                 for (int j = 1; j < 4; ++j) { h_[j] = P_[j] * h_[j - 1] + h_[j]; P_[j] = P_[j] * P_[j - 1]; }
;                 float Pg = P_[3], Hg = h_[3];
;                 { const float Pu = __shfl_up(Pg, 16), Hu = __shfl_up(Hg, 16); if (gq >= 1) { Hg = Pg * Hu + Hg; Pg = Pg * Pu; } }
;                 { const float Pu = __shfl_up(Pg, 32), Hu = __shfl_up(Hg, 32); if (gq >= 2) { Hg = Pg * Hu + Hg; Pg = Pg * Pu; } }
;                 float Pe = __shfl_up(Pg, 16), He = __shfl_up(Hg, 16); if (gq == 0) { Pe = 1.f; He = 0.f; }
;                 const float Hcm = prt ? Hc : h0s[m];
;                 const float Hin = Pe * Hcm + He, Pin = Pe * Pc;
; #pragma unroll
;                 for (int j = 0; j < 4; ++j) { hl[m][j] = h_[j] + P_[j] * Hin; pl[m][j] = P_[j] * Pin; }
;                 const float hb = __shfl(hl[m][3], 48 + fr), pb_ = __shfl(pl[m][3], 48 + fr);
;                 Hc = prt ? hb : 0.f; Pc = prt ? pb_ : 1.f;
.LBB0_415:
	v_fmamk_f32 v102, v102, 0xbfb8aa3b, v242
	v_exp_f32_e32 v102, v102
	s_mul_i32 s0, s3, 0x8400
	s_add_i32 s6, s0, 0
	s_lshl_b32 s0, s35, 2
	v_add_f32_e32 v102, 1.0, v102
	v_rcp_f32_e64 v102, -v102
	s_add_i32 s0, s6, s0
	v_lshl_add_u32 v110, v135, 2, s0
	v_add_u32_e32 v151, v110, v235
	v_mul_f32_e32 v102, v225, v102
	ds_read_b32 v110, v151
	v_mul_f32_e32 v111, 0x3f38aa3b, v102
	v_exp_f32_e32 v154, v111
	s_mov_b32 s0, 0xbe99999a
	v_cmp_nlt_f32_e32 vcc, s0, v102
	s_and_saveexec_b64 s[0:1], vcc
	s_xor_b64 s[0:1], exec, s[0:1]
	v_fma_f32 v111, -v154, v154, 1.0
	s_andn2_saveexec_b64 s[0:1], s[0:1]
	v_fmamk_f32 v111, v102, 0x39500d01, v217
	v_fmaak_f32 v111, v102, v111, 0x3c088889
	v_fmaak_f32 v111, v102, v111, 0x3d2aaaab
	v_fmaak_f32 v111, v102, v111, 0x3e2aaaab
	v_fma_f32 v111, v102, v111, 0.5
	v_fma_f32 v111, v102, v111, 1.0
	v_mul_f32_e64 v111, v111, -v102
	s_or_b64 exec, exec, s[0:1]
	v_fmamk_f32 v102, v103, 0xbfb8aa3b, v242
	v_exp_f32_e32 v102, v102
	ds_read_b32 v103, v151 offset:528
	s_mov_b32 s0, 0xbe99999a
	v_add_f32_e32 v102, 1.0, v102
	v_rcp_f32_e64 v102, -v102
	s_nop 0
	v_mul_f32_e32 v102, v225, v102
	v_mul_f32_e32 v112, 0x3f38aa3b, v102
	v_exp_f32_e32 v112, v112
	v_cmp_nlt_f32_e32 vcc, s0, v102
	s_and_saveexec_b64 s[0:1], vcc
	s_xor_b64 s[0:1], exec, s[0:1]
	v_fma_f32 v113, -v112, v112, 1.0
	s_andn2_saveexec_b64 s[0:1], s[0:1]
	v_fmamk_f32 v113, v102, 0x39500d01, v217
	v_fmaak_f32 v113, v102, v113, 0x3c088889
	v_fmaak_f32 v113, v102, v113, 0x3d2aaaab
	v_fmaak_f32 v113, v102, v113, 0x3e2aaaab
	v_fma_f32 v113, v102, v113, 0.5
	v_fma_f32 v113, v102, v113, 1.0
	v_mul_f32_e64 v113, v113, -v102
	s_or_b64 exec, exec, s[0:1]
	v_fmamk_f32 v102, v104, 0xbfb8aa3b, v242
	v_exp_f32_e32 v102, v102
	ds_read_b32 v114, v151 offset:1056
	s_mov_b32 s0, 0xbe99999a
	v_add_f32_e32 v102, 1.0, v102
	v_rcp_f32_e64 v102, -v102
	s_nop 0
	v_mul_f32_e32 v102, v225, v102
	v_mul_f32_e32 v104, 0x3f38aa3b, v102
	v_exp_f32_e32 v104, v104
	v_cmp_nlt_f32_e32 vcc, s0, v102
	s_and_saveexec_b64 s[0:1], vcc
	s_xor_b64 s[0:1], exec, s[0:1]
	v_fma_f32 v115, -v104, v104, 1.0
	s_andn2_saveexec_b64 s[0:1], s[0:1]
	v_fmamk_f32 v115, v102, 0x39500d01, v217
	v_fmaak_f32 v115, v102, v115, 0x3c088889
	v_fmaak_f32 v115, v102, v115, 0x3d2aaaab
	v_fmaak_f32 v115, v102, v115, 0x3e2aaaab
	v_fma_f32 v115, v102, v115, 0.5
	v_fma_f32 v115, v102, v115, 1.0
	v_mul_f32_e64 v115, v115, -v102
	s_or_b64 exec, exec, s[0:1]
	v_fmamk_f32 v102, v105, 0xbfb8aa3b, v242
	v_exp_f32_e32 v102, v102
	ds_read_b32 v105, v151 offset:1584
	s_mov_b32 s0, 0xbe99999a
	v_add_f32_e32 v102, 1.0, v102
	v_rcp_f32_e64 v102, -v102
	s_nop 0
	v_mul_f32_e32 v117, v225, v102
	v_mul_f32_e32 v102, 0x3f38aa3b, v117
	v_exp_f32_e32 v102, v102
	v_cmp_nlt_f32_e32 vcc, s0, v117
	s_and_saveexec_b64 s[0:1], vcc
	s_xor_b64 s[0:1], exec, s[0:1]
	v_fma_f32 v116, -v102, v102, 1.0
	s_andn2_saveexec_b64 s[0:1], s[0:1]
	v_fmamk_f32 v116, v117, 0x39500d01, v217
	v_fmaak_f32 v116, v117, v116, 0x3c088889
	v_fmaak_f32 v116, v117, v116, 0x3d2aaaab
	v_fmaak_f32 v116, v117, v116, 0x3e2aaaab
	v_fma_f32 v116, v117, v116, 0.5
	v_fma_f32 v116, v117, v116, 1.0
	v_mul_f32_e64 v116, v116, -v117
	s_or_b64 exec, exec, s[0:1]
	v_pk_fma_f32 v[98:99], v[98:99], s[98:99], v[242:243] op_sel:[0,0,1] op_sel_hi:[1,1,1]
	v_pk_fma_f32 v[100:101], v[100:101], s[98:99], v[242:243] op_sel:[0,0,1] op_sel_hi:[1,1,1]
	v_exp_f32_e32 v98, v98
	v_exp_f32_e32 v99, v99
	v_exp_f32_e32 v100, v100
	v_exp_f32_e32 v101, v101
	v_pk_add_f32 v[98:99], v[98:99], v[244:245] op_sel_hi:[1,0]
	v_pk_add_f32 v[100:101], v[100:101], v[244:245] op_sel_hi:[1,0]
	v_rcp_f32_e32 v99, v99
	v_rcp_f32_e32 v98, v98
	v_rcp_f32_e32 v100, v100
	v_sqrt_f32_e32 v113, v113
	v_sqrt_f32_e32 v111, v111
	v_sqrt_f32_e32 v115, v115
	v_rcp_f32_e32 v101, v101
	s_waitcnt lgkmcnt(2)
	v_mul_f32_e32 v99, v99, v103
	v_sqrt_f32_e32 v103, v116
	v_mul_f32_e32 v98, v98, v110
	s_waitcnt lgkmcnt(1)
	v_mul_f32_e32 v100, v100, v114
	v_mul_f32_e32 v177, v99, v113
	v_mul_f32_e32 v176, v98, v111
	v_mul_f32_e32 v100, v100, v115
	s_waitcnt lgkmcnt(0)
	v_mul_f32_e32 v101, v101, v105
	v_fmac_f32_e32 v177, v112, v176
	v_mul_f32_e32 v155, v112, v154
	v_fmac_f32_e32 v100, v104, v177
	v_mul_f32_e32 v98, v103, v101
	v_mul_f32_e32 v104, v104, v155
	v_pk_fma_f32 v[98:99], v[102:103], v[100:101], v[98:99] op_sel_hi:[1,1,0]
	v_mul_f32_e32 v105, v102, v104
	ds_bpermute_b32 v99, v229, v98
	ds_bpermute_b32 v101, v229, v105
	v_cmp_eq_u32_e32 vcc, 0, v107
	v_cmp_lt_u32_e64 s[44:45], 1, v107
	s_waitcnt lgkmcnt(1)
	v_fma_f32 v99, v105, v99, v98
	s_waitcnt lgkmcnt(0)
	v_mul_f32_e32 v101, v105, v101
	v_cndmask_b32_e32 v99, v99, v98, vcc
	v_cndmask_b32_e32 v101, v101, v105, vcc
	ds_bpermute_b32 v102, v230, v99
	ds_bpermute_b32 v103, v230, v101
	v_fmamk_f32 v94, v94, 0xbfb8aa3b, v242
	v_exp_f32_e32 v94, v94
	s_mov_b32 s0, 0xbe99999a
	s_waitcnt lgkmcnt(1)
	v_fma_f32 v102, v101, v102, v99
	s_waitcnt lgkmcnt(0)
	v_mul_f32_e32 v103, v101, v103
	v_cndmask_b32_e64 v99, v99, v102, s[44:45]
	v_cndmask_b32_e64 v101, v101, v103, s[44:45]
	ds_bpermute_b32 v99, v229, v99
	ds_bpermute_b32 v101, v229, v101
	v_add_f32_e32 v94, 1.0, v94
	v_rcp_f32_e64 v94, -v94
	v_mov_b32_e32 v103, v98
	s_waitcnt lgkmcnt(1)
	v_cndmask_b32_e64 v178, v99, 0, vcc
	s_waitcnt lgkmcnt(0)
	v_cndmask_b32_e64 v158, v101, 1.0, vcc
	s_waitcnt vmcnt(3)
; __device__ __forceinline__ float mix_sigmoid(float v) { return __builtin_amdgcn_rcpf(1.0f + __expf(-v)); }
; __device__ __forceinline__ void mix_phase(LAS unsigned char* lds, const Params& p, const int layer) {
;     ...
;                 for (int j = 0; j < 4; ++j) { const float xa = XC[(m * 16 + fq * 4 + j) * 132 + cw + fr];
;                     const float rg = mix_sigmoid(accr[m][j] + bav), ig = mix_sigmoid(acci[m][j] + bxv), la = -rg * c8v, x2 = 2.0f * la;
;                     const float Pj = __expf(la);
;                     const float q_ = 1.f + x2 * (0.5f + x2 * (1.f / 6 + x2 * (1.f / 24 + x2 * (1.f / 120 + x2 * (1.f / 720 + x2 * (1.f / 5040))))));
;                     const float om = (x2 > -0.3f) ? -x2 * q_ : 1.0f - Pj * Pj;
;                     P_[j] = Pj; h_[j] = __builtin_amdgcn_sqrtf(om) * (ig * xa); }
; #pragma unroll
;                 for (int j = 1; j < 4; ++j) { h_[j] = P_[j] * h_[j - 1] + h_[j]; P_[j] = P_[j] * P_[j - 1]; }
;                 float Pg = P_[3], Hg = h_[3];
;                 { const float Pu = __shfl_up(Pg, 16), Hu = __shfl_up(Hg, 16); if (gq >= 1) { Hg = Pg * Hu + Hg; Pg = Pg * Pu; } }
;                 { const float Pu = __shfl_up(Pg, 32), Hu = __shfl_up(Hg, 32); if (gq >= 2) { Hg = Pg * Hu + Hg; Pg = Pg * Pu; } }
;                 float Pe = __shfl_up(Pg, 16), He = __shfl_up(Hg, 16); if (gq == 0) { Pe = 1.f; He = 0.f; }
;                 const float Hcm = prt ? Hc : h0s[m];
;                 const float Hin = Pe * Hcm + He, Pin = Pe * Pc;
; #pragma unroll
;                 for (int j = 0; j < 4; ++j) { hl[m][j] = h_[j] + P_[j] * Hin; pl[m][j] = P_[j] * Pin; }
;                 const float hb = __shfl(hl[m][3], 48 + fr), pb_ = __shfl(pl[m][3], 48 + fr);
;                 Hc = prt ? hb : 0.f; Pc = prt ? pb_ : 1.f;
	v_fmac_f32_e32 v178, v109, v158
	v_mul_f32_e32 v102, v104, v178
	v_mul_f32_e32 v101, v105, v178
	v_pk_add_f32 v[156:157], v[102:103], v[100:101]
	v_pk_mul_f32 v[160:161], v[104:105], v[158:159] op_sel_hi:[1,0]
	v_mul_f32_e32 v94, v225, v94
	ds_bpermute_b32 v98, v232, v157
	ds_bpermute_b32 v99, v232, v161
	ds_read_b32 v100, v151 offset:8448
	v_mul_f32_e32 v101, 0x3f38aa3b, v94
	v_exp_f32_e32 v162, v101
	v_cmp_nlt_f32_e64 s[0:1], s0, v94
	s_and_saveexec_b64 s[14:15], s[0:1]
	s_xor_b64 s[0:1], exec, s[14:15]
	v_fma_f32 v101, -v162, v162, 1.0
	s_andn2_saveexec_b64 s[0:1], s[0:1]
	v_fmamk_f32 v101, v94, 0x39500d01, v217
	v_fmaak_f32 v101, v94, v101, 0x3c088889
	v_fmaak_f32 v101, v94, v101, 0x3d2aaaab
	v_fmaak_f32 v101, v94, v101, 0x3e2aaaab
	v_fma_f32 v101, v94, v101, 0.5
	v_fma_f32 v101, v94, v101, 1.0
	v_mul_f32_e64 v101, v101, -v94
	s_or_b64 exec, exec, s[0:1]
	v_fmamk_f32 v94, v95, 0xbfb8aa3b, v242
	v_exp_f32_e32 v94, v94
	ds_read_b32 v95, v151 offset:8976
	s_mov_b32 s0, 0xbe99999a
	v_add_f32_e32 v94, 1.0, v94
	v_rcp_f32_e64 v94, -v94
	s_nop 0
	v_mul_f32_e32 v94, v225, v94
	v_mul_f32_e32 v102, 0x3f38aa3b, v94
	v_exp_f32_e32 v102, v102
	v_cmp_nlt_f32_e64 s[0:1], s0, v94
	s_and_saveexec_b64 s[14:15], s[0:1]
	s_xor_b64 s[0:1], exec, s[14:15]
	v_fma_f32 v103, -v102, v102, 1.0
	s_andn2_saveexec_b64 s[0:1], s[0:1]
	v_fmamk_f32 v103, v94, 0x39500d01, v217
	v_fmaak_f32 v103, v94, v103, 0x3c088889
	v_fmaak_f32 v103, v94, v103, 0x3d2aaaab
	v_fmaak_f32 v103, v94, v103, 0x3e2aaaab
	v_fma_f32 v103, v94, v103, 0.5
	v_fma_f32 v103, v94, v103, 1.0
	v_mul_f32_e64 v103, v103, -v94
	s_or_b64 exec, exec, s[0:1]
	v_fmamk_f32 v94, v96, 0xbfb8aa3b, v242
	v_exp_f32_e32 v94, v94
	ds_read_b32 v104, v151 offset:9504
	s_mov_b32 s0, 0xbe99999a
	v_add_f32_e32 v94, 1.0, v94
	v_rcp_f32_e64 v94, -v94
	s_nop 0
	v_mul_f32_e32 v94, v225, v94
	v_mul_f32_e32 v96, 0x3f38aa3b, v94
	v_exp_f32_e32 v96, v96
	v_cmp_nlt_f32_e64 s[0:1], s0, v94
	s_and_saveexec_b64 s[14:15], s[0:1]
	s_xor_b64 s[0:1], exec, s[14:15]
	v_fma_f32 v105, -v96, v96, 1.0
	s_andn2_saveexec_b64 s[0:1], s[0:1]
	v_fmamk_f32 v105, v94, 0x39500d01, v217
	v_fmaak_f32 v105, v94, v105, 0x3c088889
	v_fmaak_f32 v105, v94, v105, 0x3d2aaaab
	v_fmaak_f32 v105, v94, v105, 0x3e2aaaab
	v_fma_f32 v105, v94, v105, 0.5
	v_fma_f32 v105, v94, v105, 1.0
	v_mul_f32_e64 v105, v105, -v94
	s_or_b64 exec, exec, s[0:1]
	v_fmamk_f32 v94, v97, 0xbfb8aa3b, v242
	v_exp_f32_e32 v94, v94
	ds_read_b32 v97, v151 offset:10032
	s_mov_b32 s0, 0xbe99999a
	v_add_f32_e32 v94, 1.0, v94
	v_rcp_f32_e64 v94, -v94
	s_nop 0
	v_mul_f32_e32 v109, v225, v94
	v_mul_f32_e32 v94, 0x3f38aa3b, v109
	v_exp_f32_e32 v94, v94
	v_cmp_nlt_f32_e64 s[0:1], s0, v109
	s_and_saveexec_b64 s[14:15], s[0:1]
	s_xor_b64 s[0:1], exec, s[14:15]
	v_fma_f32 v107, -v94, v94, 1.0
	s_andn2_saveexec_b64 s[0:1], s[0:1]
	v_fmamk_f32 v107, v109, 0x39500d01, v217
	v_fmaak_f32 v107, v109, v107, 0x3c088889
	v_fmaak_f32 v107, v109, v107, 0x3d2aaaab
	v_fmaak_f32 v107, v109, v107, 0x3e2aaaab
	v_fma_f32 v107, v109, v107, 0.5
	v_fma_f32 v107, v109, v107, 1.0
	v_mul_f32_e64 v107, v107, -v109
	s_or_b64 exec, exec, s[0:1]
	v_pk_fma_f32 v[90:91], v[90:91], s[98:99], v[242:243] op_sel:[0,0,1] op_sel_hi:[1,1,1]
	v_pk_fma_f32 v[92:93], v[92:93], s[98:99], v[242:243] op_sel:[0,0,1] op_sel_hi:[1,1,1]
	v_exp_f32_e32 v90, v90
	v_exp_f32_e32 v91, v91
	v_exp_f32_e32 v92, v92
	v_exp_f32_e32 v93, v93
	v_pk_add_f32 v[90:91], v[90:91], v[244:245] op_sel_hi:[1,0]
	v_pk_add_f32 v[92:93], v[92:93], v[244:245] op_sel_hi:[1,0]
	v_rcp_f32_e32 v91, v91
	v_rcp_f32_e32 v90, v90
	v_rcp_f32_e32 v92, v92
	v_sqrt_f32_e32 v103, v103
	v_sqrt_f32_e32 v101, v101
	v_sqrt_f32_e32 v105, v105
	v_rcp_f32_e32 v93, v93
	s_waitcnt lgkmcnt(2)
	v_mul_f32_e32 v91, v91, v95
	v_sqrt_f32_e32 v95, v107
	v_mul_f32_e32 v90, v90, v100
	s_waitcnt lgkmcnt(1)
	v_mul_f32_e32 v92, v92, v104
	v_mul_f32_e32 v189, v91, v103
	v_mul_f32_e32 v188, v90, v101
	v_mul_f32_e32 v92, v92, v105
	s_waitcnt lgkmcnt(0)
	v_mul_f32_e32 v93, v93, v97
	v_fmac_f32_e32 v189, v102, v188
	v_mul_f32_e32 v163, v102, v162
	v_fmac_f32_e32 v92, v96, v189
	v_mul_f32_e32 v90, v95, v93
	v_mul_f32_e32 v96, v96, v163
	v_pk_fma_f32 v[90:91], v[94:95], v[92:93], v[90:91] op_sel_hi:[1,1,0]
	v_mul_f32_e32 v97, v94, v96
	ds_bpermute_b32 v91, v229, v90
	ds_bpermute_b32 v93, v229, v97
	v_fmamk_f32 v86, v86, 0xbfb8aa3b, v242
	v_exp_f32_e32 v86, v86
	s_waitcnt lgkmcnt(1)
	v_fma_f32 v91, v97, v91, v90
	s_waitcnt lgkmcnt(0)
	v_mul_f32_e32 v93, v97, v93
	v_cndmask_b32_e32 v91, v91, v90, vcc
	v_cndmask_b32_e32 v93, v93, v97, vcc
	ds_bpermute_b32 v94, v230, v91
	ds_bpermute_b32 v95, v230, v93
	v_add_f32_e32 v86, 1.0, v86
	v_rcp_f32_e64 v86, -v86
	s_mov_b32 s0, 0xbe99999a
	s_waitcnt lgkmcnt(1)
	v_fma_f32 v94, v93, v94, v91
	s_waitcnt lgkmcnt(0)
	v_mul_f32_e32 v95, v93, v95
	v_cndmask_b32_e64 v91, v91, v94, s[44:45]
	v_cndmask_b32_e64 v93, v93, v95, s[44:45]
	ds_bpermute_b32 v91, v229, v91
	ds_bpermute_b32 v93, v229, v93
	s_waitcnt vmcnt(2)
	v_cndmask_b32_e64 v95, v108, v98, s[42:43]
	v_cndmask_b32_e64 v94, 1.0, v99, s[42:43]
	v_mul_f32_e32 v86, v225, v86
	s_waitcnt lgkmcnt(1)
	v_cndmask_b32_e64 v192, v91, 0, vcc
	s_waitcnt lgkmcnt(0)
; __device__ __forceinline__ float mix_sigmoid(float v) { return __builtin_amdgcn_rcpf(1.0f + __expf(-v)); }
; __device__ __forceinline__ void mix_phase(LAS unsigned char* lds, const Params& p, const int layer) {
;     ...
;                 for (int j = 0; j < 4; ++j) { const float xa = XC[(m * 16 + fq * 4 + j) * 132 + cw + fr];
;                     const float rg = mix_sigmoid(accr[m][j] + bav), ig = mix_sigmoid(acci[m][j] + bxv), la = -rg * c8v, x2 = 2.0f * la;
;                     const float Pj = __expf(la);
;                     const float q_ = 1.f + x2 * (0.5f + x2 * (1.f / 6 + x2 * (1.f / 24 + x2 * (1.f / 120 + x2 * (1.f / 720 + x2 * (1.f / 5040))))));
;                     const float om = (x2 > -0.3f) ? -x2 * q_ : 1.0f - Pj * Pj;
;                     P_[j] = Pj; h_[j] = __builtin_amdgcn_sqrtf(om) * (ig * xa); }
; #pragma unroll
;                 for (int j = 1; j < 4; ++j) { h_[j] = P_[j] * h_[j - 1] + h_[j]; P_[j] = P_[j] * P_[j - 1]; }
;                 float Pg = P_[3], Hg = h_[3];
;                 { const float Pu = __shfl_up(Pg, 16), Hu = __shfl_up(Hg, 16); if (gq >= 1) { Hg = Pg * Hu + Hg; Pg = Pg * Pu; } }
;                 { const float Pu = __shfl_up(Pg, 32), Hu = __shfl_up(Hg, 32); if (gq >= 2) { Hg = Pg * Hu + Hg; Pg = Pg * Pu; } }
;                 float Pe = __shfl_up(Pg, 16), He = __shfl_up(Hg, 16); if (gq == 0) { Pe = 1.f; He = 0.f; }
;                 const float Hcm = prt ? Hc : h0s[m];
;                 const float Hin = Pe * Hcm + He, Pin = Pe * Pc;
; #pragma unroll
;                 for (int j = 0; j < 4; ++j) { hl[m][j] = h_[j] + P_[j] * Hin; pl[m][j] = P_[j] * Pin; }
;                 const float hb = __shfl(hl[m][3], 48 + fr), pb_ = __shfl(pl[m][3], 48 + fr);
;                 Hc = prt ? hb : 0.f; Pc = prt ? pb_ : 1.f;
	v_cndmask_b32_e64 v91, v93, 1.0, vcc
	v_fmac_f32_e32 v192, v95, v91
	v_mul_f32_e32 v170, v94, v91
	v_mul_f32_e32 v94, v96, v192
	v_mul_f32_e32 v93, v97, v192
	v_mov_b32_e32 v95, v90
	v_pk_add_f32 v[168:169], v[94:95], v[92:93]
	v_pk_mul_f32 v[172:173], v[96:97], v[170:171] op_sel_hi:[1,0]
	ds_bpermute_b32 v90, v232, v169
	ds_bpermute_b32 v91, v232, v173
	ds_read_b32 v92, v151 offset:16896
	v_mul_f32_e32 v93, 0x3f38aa3b, v86
	v_exp_f32_e32 v174, v93
	v_cmp_nlt_f32_e64 s[0:1], s0, v86
	s_and_saveexec_b64 s[14:15], s[0:1]
	s_xor_b64 s[0:1], exec, s[14:15]
	v_fma_f32 v93, -v174, v174, 1.0
	s_andn2_saveexec_b64 s[0:1], s[0:1]
	v_fmamk_f32 v93, v86, 0x39500d01, v217
	v_fmaak_f32 v93, v86, v93, 0x3c088889
	v_fmaak_f32 v93, v86, v93, 0x3d2aaaab
	v_fmaak_f32 v93, v86, v93, 0x3e2aaaab
	v_fma_f32 v93, v86, v93, 0.5
	v_fma_f32 v93, v86, v93, 1.0
	v_mul_f32_e64 v93, v93, -v86
	s_or_b64 exec, exec, s[0:1]
	v_fmamk_f32 v86, v87, 0xbfb8aa3b, v242
	v_exp_f32_e32 v86, v86
	ds_read_b32 v87, v151 offset:17424
	s_mov_b32 s0, 0xbe99999a
	v_add_f32_e32 v86, 1.0, v86
	v_rcp_f32_e64 v86, -v86
	s_nop 0
	v_mul_f32_e32 v86, v225, v86
	v_mul_f32_e32 v94, 0x3f38aa3b, v86
	v_exp_f32_e32 v94, v94
	v_cmp_nlt_f32_e64 s[0:1], s0, v86
	s_and_saveexec_b64 s[14:15], s[0:1]
	s_xor_b64 s[0:1], exec, s[14:15]
	v_fma_f32 v95, -v94, v94, 1.0
	s_andn2_saveexec_b64 s[0:1], s[0:1]
	v_fmamk_f32 v95, v86, 0x39500d01, v217
	v_fmaak_f32 v95, v86, v95, 0x3c088889
	v_fmaak_f32 v95, v86, v95, 0x3d2aaaab
	v_fmaak_f32 v95, v86, v95, 0x3e2aaaab
	v_fma_f32 v95, v86, v95, 0.5
	v_fma_f32 v95, v86, v95, 1.0
	v_mul_f32_e64 v95, v95, -v86
	s_or_b64 exec, exec, s[0:1]
	v_fmamk_f32 v86, v88, 0xbfb8aa3b, v242
	v_exp_f32_e32 v86, v86
	ds_read_b32 v96, v151 offset:17952
	s_mov_b32 s0, 0xbe99999a
	v_add_f32_e32 v86, 1.0, v86
	v_rcp_f32_e64 v86, -v86
	s_nop 0
	v_mul_f32_e32 v86, v225, v86
	v_mul_f32_e32 v88, 0x3f38aa3b, v86
	v_exp_f32_e32 v88, v88
	v_cmp_nlt_f32_e64 s[0:1], s0, v86
	s_and_saveexec_b64 s[14:15], s[0:1]
	s_xor_b64 s[0:1], exec, s[14:15]
	v_fma_f32 v97, -v88, v88, 1.0
	s_andn2_saveexec_b64 s[0:1], s[0:1]
	v_fmamk_f32 v97, v86, 0x39500d01, v217
	v_fmaak_f32 v97, v86, v97, 0x3c088889
	v_fmaak_f32 v97, v86, v97, 0x3d2aaaab
	v_fmaak_f32 v97, v86, v97, 0x3e2aaaab
	v_fma_f32 v97, v86, v97, 0.5
	v_fma_f32 v97, v86, v97, 1.0
	v_mul_f32_e64 v97, v97, -v86
	s_or_b64 exec, exec, s[0:1]
	v_fmamk_f32 v86, v89, 0xbfb8aa3b, v242
	v_exp_f32_e32 v86, v86
	ds_read_b32 v89, v151 offset:18480
	s_mov_b32 s0, 0xbe99999a
	v_add_f32_e32 v86, 1.0, v86
	v_rcp_f32_e64 v86, -v86
	s_nop 0
	v_mul_f32_e32 v99, v225, v86
	v_mul_f32_e32 v86, 0x3f38aa3b, v99
	v_exp_f32_e32 v86, v86
	v_cmp_nlt_f32_e64 s[0:1], s0, v99
	s_and_saveexec_b64 s[14:15], s[0:1]
	s_xor_b64 s[0:1], exec, s[14:15]
	v_fma_f32 v98, -v86, v86, 1.0
	s_andn2_saveexec_b64 s[0:1], s[0:1]
	v_fmamk_f32 v98, v99, 0x39500d01, v217
	v_fmaak_f32 v98, v99, v98, 0x3c088889
	v_fmaak_f32 v98, v99, v98, 0x3d2aaaab
	v_fmaak_f32 v98, v99, v98, 0x3e2aaaab
	v_fma_f32 v98, v99, v98, 0.5
	v_fma_f32 v98, v99, v98, 1.0
	v_mul_f32_e64 v98, v98, -v99
	s_or_b64 exec, exec, s[0:1]
	v_pk_fma_f32 v[82:83], v[82:83], s[98:99], v[242:243] op_sel:[0,0,1] op_sel_hi:[1,1,1]
	v_pk_fma_f32 v[84:85], v[84:85], s[98:99], v[242:243] op_sel:[0,0,1] op_sel_hi:[1,1,1]
	v_exp_f32_e32 v82, v82
	v_exp_f32_e32 v83, v83
	v_exp_f32_e32 v84, v84
	v_exp_f32_e32 v85, v85
	v_pk_add_f32 v[82:83], v[82:83], v[244:245] op_sel_hi:[1,0]
	v_pk_add_f32 v[84:85], v[84:85], v[244:245] op_sel_hi:[1,0]
	v_rcp_f32_e32 v83, v83
	v_rcp_f32_e32 v82, v82
	v_rcp_f32_e32 v84, v84
	v_sqrt_f32_e32 v95, v95
	v_sqrt_f32_e32 v93, v93
	v_sqrt_f32_e32 v97, v97
	v_rcp_f32_e32 v85, v85
	s_waitcnt lgkmcnt(2)
	v_mul_f32_e32 v83, v83, v87
	v_sqrt_f32_e32 v87, v98
	v_mul_f32_e32 v82, v82, v92
	s_waitcnt lgkmcnt(1)
	v_mul_f32_e32 v84, v84, v96
	v_mul_f32_e32 v201, v83, v95
	v_mul_f32_e32 v200, v82, v93
	v_mul_f32_e32 v84, v84, v97
	s_waitcnt lgkmcnt(0)
	v_mul_f32_e32 v85, v85, v89
	v_fmac_f32_e32 v201, v94, v200
	v_mul_f32_e32 v175, v94, v174
	v_fmac_f32_e32 v84, v88, v201
	v_mul_f32_e32 v82, v87, v85
	v_mul_f32_e32 v88, v88, v175
	v_pk_fma_f32 v[82:83], v[86:87], v[84:85], v[82:83] op_sel_hi:[1,1,0]
	v_mul_f32_e32 v89, v86, v88
	ds_bpermute_b32 v83, v229, v82
	ds_bpermute_b32 v85, v229, v89
	v_fmamk_f32 v78, v78, 0xbfb8aa3b, v242
	v_exp_f32_e32 v78, v78
	s_waitcnt lgkmcnt(1)
	v_fma_f32 v83, v89, v83, v82
	s_waitcnt lgkmcnt(0)
	v_mul_f32_e32 v85, v89, v85
	v_cndmask_b32_e32 v83, v83, v82, vcc
	v_cndmask_b32_e32 v85, v85, v89, vcc
	ds_bpermute_b32 v86, v230, v83
	ds_bpermute_b32 v87, v230, v85
	v_add_f32_e32 v78, 1.0, v78
	v_rcp_f32_e64 v78, -v78
	s_mov_b32 s0, 0xbe99999a
	s_waitcnt lgkmcnt(1)
	v_fma_f32 v86, v85, v86, v83
	s_waitcnt lgkmcnt(0)
	v_mul_f32_e32 v87, v85, v87
	v_cndmask_b32_e64 v83, v83, v86, s[44:45]
	v_cndmask_b32_e64 v85, v85, v87, s[44:45]
	ds_bpermute_b32 v83, v229, v83
	ds_bpermute_b32 v85, v229, v85
	s_waitcnt vmcnt(1)
	v_cndmask_b32_e64 v87, v106, v90, s[42:43]
	v_cndmask_b32_e64 v86, 1.0, v91, s[42:43]
	v_mul_f32_e32 v78, v225, v78
	s_waitcnt lgkmcnt(1)
	v_cndmask_b32_e64 v202, v83, 0, vcc
	s_waitcnt lgkmcnt(0)
; __device__ __forceinline__ float mix_sigmoid(float v) { return __builtin_amdgcn_rcpf(1.0f + __expf(-v)); }
; __device__ __forceinline__ void mix_phase(LAS unsigned char* lds, const Params& p, const int layer) {
;     ...
;                 for (int j = 0; j < 4; ++j) { const float xa = XC[(m * 16 + fq * 4 + j) * 132 + cw + fr];
;                     const float rg = mix_sigmoid(accr[m][j] + bav), ig = mix_sigmoid(acci[m][j] + bxv), la = -rg * c8v, x2 = 2.0f * la;
;                     const float Pj = __expf(la);
;                     const float q_ = 1.f + x2 * (0.5f + x2 * (1.f / 6 + x2 * (1.f / 24 + x2 * (1.f / 120 + x2 * (1.f / 720 + x2 * (1.f / 5040))))));
;                     const float om = (x2 > -0.3f) ? -x2 * q_ : 1.0f - Pj * Pj;
;                     P_[j] = Pj; h_[j] = __builtin_amdgcn_sqrtf(om) * (ig * xa); }
; #pragma unroll
;                 for (int j = 1; j < 4; ++j) { h_[j] = P_[j] * h_[j - 1] + h_[j]; P_[j] = P_[j] * P_[j - 1]; }
;                 float Pg = P_[3], Hg = h_[3];
;                 { const float Pu = __shfl_up(Pg, 16), Hu = __shfl_up(Hg, 16); if (gq >= 1) { Hg = Pg * Hu + Hg; Pg = Pg * Pu; } }
;                 { const float Pu = __shfl_up(Pg, 32), Hu = __shfl_up(Hg, 32); if (gq >= 2) { Hg = Pg * Hu + Hg; Pg = Pg * Pu; } }
;                 float Pe = __shfl_up(Pg, 16), He = __shfl_up(Hg, 16); if (gq == 0) { Pe = 1.f; He = 0.f; }
;                 const float Hcm = prt ? Hc : h0s[m];
;                 const float Hin = Pe * Hcm + He, Pin = Pe * Pc;
; #pragma unroll
;                 for (int j = 0; j < 4; ++j) { hl[m][j] = h_[j] + P_[j] * Hin; pl[m][j] = P_[j] * Pin; }
;                 const float hb = __shfl(hl[m][3], 48 + fr), pb_ = __shfl(pl[m][3], 48 + fr);
;                 Hc = prt ? hb : 0.f; Pc = prt ? pb_ : 1.f;
;             }
;             if (!prt && (fq & 1)) {
; #pragma unroll
;                 for (int m = 0; m < 4; ++m) out[O_HS + (size_t)(layer * 128 + ((r0 - NP) >> 3) + 2 * m + (fq >> 1)) * LW + ch] = hl[m][3];
	v_cndmask_b32_e64 v83, v85, 1.0, vcc
	v_fmac_f32_e32 v202, v87, v83
	v_mul_f32_e32 v182, v86, v83
	v_mul_f32_e32 v86, v88, v202
	v_mul_f32_e32 v85, v89, v202
	v_mov_b32_e32 v87, v82
	v_pk_add_f32 v[180:181], v[86:87], v[84:85]
	v_pk_mul_f32 v[184:185], v[88:89], v[182:183] op_sel_hi:[1,0]
	ds_bpermute_b32 v82, v232, v181
	ds_bpermute_b32 v83, v232, v185
	ds_read_b32 v84, v151 offset:25344
	v_mul_f32_e32 v85, 0x3f38aa3b, v78
	v_exp_f32_e32 v186, v85
	v_cmp_nlt_f32_e64 s[0:1], s0, v78
	s_and_saveexec_b64 s[14:15], s[0:1]
	s_xor_b64 s[0:1], exec, s[14:15]
	v_fma_f32 v85, -v186, v186, 1.0
	s_andn2_saveexec_b64 s[0:1], s[0:1]
	v_fmamk_f32 v85, v78, 0x39500d01, v217
	v_fmaak_f32 v85, v78, v85, 0x3c088889
	v_fmaak_f32 v85, v78, v85, 0x3d2aaaab
	v_fmaak_f32 v85, v78, v85, 0x3e2aaaab
	v_fma_f32 v85, v78, v85, 0.5
	v_fma_f32 v85, v78, v85, 1.0
	v_mul_f32_e64 v85, v85, -v78
	s_or_b64 exec, exec, s[0:1]
	v_fmamk_f32 v78, v79, 0xbfb8aa3b, v242
	v_exp_f32_e32 v78, v78
	ds_read_b32 v79, v151 offset:25872
	s_mov_b32 s0, 0xbe99999a
	v_add_f32_e32 v78, 1.0, v78
	v_rcp_f32_e64 v78, -v78
	s_nop 0
	v_mul_f32_e32 v78, v225, v78
	v_mul_f32_e32 v86, 0x3f38aa3b, v78
	v_exp_f32_e32 v86, v86
	v_cmp_nlt_f32_e64 s[0:1], s0, v78
	s_and_saveexec_b64 s[14:15], s[0:1]
	s_xor_b64 s[0:1], exec, s[14:15]
	v_fma_f32 v87, -v86, v86, 1.0
	s_andn2_saveexec_b64 s[0:1], s[0:1]
	v_fmamk_f32 v87, v78, 0x39500d01, v217
	v_fmaak_f32 v87, v78, v87, 0x3c088889
	v_fmaak_f32 v87, v78, v87, 0x3d2aaaab
	v_fmaak_f32 v87, v78, v87, 0x3e2aaaab
	v_fma_f32 v87, v78, v87, 0.5
	v_fma_f32 v87, v78, v87, 1.0
	v_mul_f32_e64 v87, v87, -v78
	s_or_b64 exec, exec, s[0:1]
	v_fmamk_f32 v78, v80, 0xbfb8aa3b, v242
	v_exp_f32_e32 v78, v78
	ds_read_b32 v88, v151 offset:26400
	s_mov_b32 s0, 0xbe99999a
	v_add_f32_e32 v78, 1.0, v78
	v_rcp_f32_e64 v78, -v78
	s_nop 0
	v_mul_f32_e32 v78, v225, v78
	v_mul_f32_e32 v80, 0x3f38aa3b, v78
	v_exp_f32_e32 v80, v80
	v_cmp_nlt_f32_e64 s[0:1], s0, v78
	s_and_saveexec_b64 s[14:15], s[0:1]
	s_xor_b64 s[0:1], exec, s[14:15]
	v_fma_f32 v89, -v80, v80, 1.0
	s_andn2_saveexec_b64 s[0:1], s[0:1]
	v_fmamk_f32 v89, v78, 0x39500d01, v217
	v_fmaak_f32 v89, v78, v89, 0x3c088889
	v_fmaak_f32 v89, v78, v89, 0x3d2aaaab
	v_fmaak_f32 v89, v78, v89, 0x3e2aaaab
	v_fma_f32 v89, v78, v89, 0.5
	v_fma_f32 v89, v78, v89, 1.0
	v_mul_f32_e64 v89, v89, -v78
	s_or_b64 exec, exec, s[0:1]
	v_fmamk_f32 v78, v81, 0xbfb8aa3b, v242
	v_exp_f32_e32 v78, v78
	ds_read_b32 v81, v151 offset:26928
	s_mov_b32 s0, 0xbe99999a
	v_add_f32_e32 v78, 1.0, v78
	v_rcp_f32_e64 v78, -v78
	s_nop 0
	v_mul_f32_e32 v91, v225, v78
	v_mul_f32_e32 v78, 0x3f38aa3b, v91
	v_exp_f32_e32 v78, v78
	v_cmp_nlt_f32_e64 s[0:1], s0, v91
	s_and_saveexec_b64 s[14:15], s[0:1]
	s_xor_b64 s[0:1], exec, s[14:15]
	v_fma_f32 v90, -v78, v78, 1.0
	s_andn2_saveexec_b64 s[0:1], s[0:1]
	v_fmamk_f32 v90, v91, 0x39500d01, v217
	v_fmaak_f32 v90, v91, v90, 0x3c088889
	v_fmaak_f32 v90, v91, v90, 0x3d2aaaab
	v_fmaak_f32 v90, v91, v90, 0x3e2aaaab
	v_fma_f32 v90, v91, v90, 0.5
	v_fma_f32 v90, v91, v90, 1.0
	v_mul_f32_e64 v90, v90, -v91
	s_or_b64 exec, exec, s[0:1]
	v_pk_fma_f32 v[74:75], v[74:75], s[98:99], v[242:243] op_sel:[0,0,1] op_sel_hi:[1,1,1]
	v_pk_fma_f32 v[76:77], v[76:77], s[98:99], v[242:243] op_sel:[0,0,1] op_sel_hi:[1,1,1]
	v_exp_f32_e32 v74, v74
	v_exp_f32_e32 v75, v75
	v_exp_f32_e32 v76, v76
	v_exp_f32_e32 v77, v77
	v_pk_add_f32 v[74:75], v[74:75], v[244:245] op_sel_hi:[1,0]
	v_pk_add_f32 v[76:77], v[76:77], v[244:245] op_sel_hi:[1,0]
	v_rcp_f32_e32 v75, v75
	v_rcp_f32_e32 v74, v74
	v_rcp_f32_e32 v76, v76
	v_sqrt_f32_e32 v87, v87
	v_sqrt_f32_e32 v85, v85
	v_sqrt_f32_e32 v89, v89
	v_rcp_f32_e32 v77, v77
	s_waitcnt lgkmcnt(2)
	v_mul_f32_e32 v75, v75, v79
	v_sqrt_f32_e32 v79, v90
	v_mul_f32_e32 v74, v74, v84
	s_waitcnt lgkmcnt(1)
	v_mul_f32_e32 v76, v76, v88
	v_mul_f32_e32 v205, v75, v87
	v_mul_f32_e32 v204, v74, v85
	v_mul_f32_e32 v76, v76, v89
	s_waitcnt lgkmcnt(0)
	v_mul_f32_e32 v77, v77, v81
	v_fmac_f32_e32 v205, v86, v204
	v_mul_f32_e32 v187, v86, v186
	v_fmac_f32_e32 v76, v80, v205
	v_mul_f32_e32 v74, v79, v77
	v_mul_f32_e32 v80, v80, v187
	v_pk_fma_f32 v[74:75], v[78:79], v[76:77], v[74:75] op_sel_hi:[1,1,0]
	v_mul_f32_e32 v81, v78, v80
	ds_bpermute_b32 v75, v229, v74
	ds_bpermute_b32 v77, v229, v81
	s_waitcnt vmcnt(0)
	v_cndmask_b32_e64 v0, v0, v82, s[42:43]
	s_nor_b64 s[14:15], s[42:43], s[38:39]
	s_waitcnt lgkmcnt(1)
	v_fma_f32 v75, v81, v75, v74
	s_waitcnt lgkmcnt(0)
	v_mul_f32_e32 v77, v81, v77
	v_cndmask_b32_e32 v75, v75, v74, vcc
	v_cndmask_b32_e32 v77, v77, v81, vcc
	ds_bpermute_b32 v78, v230, v75
	ds_bpermute_b32 v79, v230, v77
	s_waitcnt lgkmcnt(1)
	v_fma_f32 v78, v77, v78, v75
	s_waitcnt lgkmcnt(0)
	v_mul_f32_e32 v79, v77, v79
	v_cndmask_b32_e64 v75, v75, v78, s[44:45]
	v_cndmask_b32_e64 v77, v77, v79, s[44:45]
	ds_bpermute_b32 v75, v229, v75
	ds_bpermute_b32 v77, v229, v77
	v_cndmask_b32_e64 v78, 1.0, v83, s[42:43]
	v_mov_b32_e32 v79, v74
	s_waitcnt lgkmcnt(1)
	v_cndmask_b32_e64 v206, v75, 0, vcc
	s_waitcnt lgkmcnt(0)
	v_cndmask_b32_e64 v75, v77, 1.0, vcc
	v_fmac_f32_e32 v206, v0, v75
	v_mul_f32_e32 v196, v78, v75
	v_mul_f32_e32 v78, v80, v206
	v_mul_f32_e32 v77, v81, v206
	v_pk_add_f32 v[190:191], v[78:79], v[76:77]
	v_pk_mul_f32 v[194:195], v[80:81], v[196:197] op_sel_hi:[1,0]
	ds_bpermute_b32 v199, v232, v191
	ds_bpermute_b32 v241, v232, v195
	s_and_saveexec_b64 s[0:1], s[14:15]
	s_cbranch_execz .LBB0_481
	s_add_i32 s13, s7, 0xffffe000
	s_ashr_i32 s13, s13, 3
	v_add_u32_e32 v74, s13, v228
	v_ashrrev_i32_e32 v75, 31, v74
	v_readlane_b32 s44, v251, 1
	v_lshlrev_b64 v[74:75], 13, v[74:75]
	v_readlane_b32 s46, v251, 3
	v_readlane_b32 s47, v251, 4
	v_readlane_b32 s45, v251, 2
	v_readlane_b32 s48, v251, 5
	v_lshl_add_u64 v[74:75], s[46:47], 0, v[74:75]
	v_lshl_add_u64 v[74:75], v[132:133], 2, v[74:75]
	v_add_co_u32_e32 v76, vcc, 0x5db8000, v74
	v_readlane_b32 s49, v251, 6
	s_nop 0
	v_addc_co_u32_e32 v77, vcc, 0, v75, vcc
	global_store_dword v[76:77], v157, off
	v_add_co_u32_e32 v76, vcc, 0x5dbc000, v74
	v_readlane_b32 s50, v251, 7
	s_nop 0
	v_addc_co_u32_e32 v77, vcc, 0, v75, vcc
	global_store_dword v[76:77], v169, off
	v_add_co_u32_e32 v76, vcc, 0x5dc0000, v74
	v_readlane_b32 s51, v251, 8
	s_nop 0
	v_addc_co_u32_e32 v77, vcc, 0, v75, vcc
	v_add_co_u32_e32 v74, vcc, 0x5dc4000, v74
	global_store_dword v[76:77], v181, off
	s_nop 0
	v_addc_co_u32_e32 v75, vcc, 0, v75, vcc
	global_store_dword v[74:75], v191, off
